# split-phase first grid barrier: arrive after P0, run mod-independent P1 items, then observe the release; no L2 write-back at that seam
# speedup vs baseline: 1.0072x; 1.0072x over previous
; __device__ __forceinline__ unsigned xb_ld(unsigned* p)              { return __hip_atomic_load(p, __ATOMIC_RELAXED, __HIP_MEMORY_SCOPE_AGENT); }
; __device__ __forceinline__ unsigned xb_add(unsigned* p, unsigned v) { return __hip_atomic_fetch_add(p, v, __ATOMIC_RELAXED, __HIP_MEMORY_SCOPE_AGENT); }
; #define XB_SPIN(cond, bar) do { unsigned _sp = 0; while (cond) { __builtin_amdgcn_s_sleep(1); \
;     if ((++_sp & 255u) == 0u) { if (xb_ld(&(bar)[XB_TMO])) break; if (_sp > XB_SPIN_CAP) { atomicAdd(&(bar)[XB_TMO], 1u); break; } } } } while (0)
; __device__ __forceinline__ void xcd_barrier(const XcdBarrier& b) {
;     ...
;         const unsigned old = xb_add(&bar[XB_XSUB(b.x)], 1u);
;         const unsigned gen = old / nloc;
;         if (old + 1u == (gen + 1u) * nloc) {
;             __builtin_amdgcn_fence(__ATOMIC_RELEASE, "agent");
;             asm volatile("s_waitcnt vmcnt(0)" ::: "memory");
;             const unsigned og = xb_add(&bar[XB_TOP], 1u);
;             const unsigned tg = og / nx;
;             if (og + 1u == (tg + 1u) * nx) xb_add(&bar[XB_TOPGEN], 1u);
;             else XB_SPIN(xb_ld(&bar[XB_TOPGEN]) == tg, bar);
;             __builtin_amdgcn_fence(__ATOMIC_ACQUIRE, "agent");
;             xb_add(&bar[XB_XGEN(b.x)], 1u);
;             asm volatile("s_waitcnt vmcnt(0)" ::: "memory");
;         } else {
;             XB_SPIN(xb_ld(&bar[XB_XGEN(b.x)]) == gen, bar);
;             __builtin_amdgcn_fence(__ATOMIC_ACQUIRE, "agent");
;             asm volatile("s_waitcnt vmcnt(0)" ::: "memory");
;         }
.LBB0_31:
	s_or_b64 exec, exec, s[10:11]
	v_cvt_f32_u32_e32 v5, v3
	s_waitcnt vmcnt(0)
	v_readfirstlane_b32 s8, v4
	v_sub_u32_e32 v4, 0, v3
	v_rcp_iflag_f32_e32 v5, v5
	v_add_u32_e32 v6, s8, v2
	v_mul_f32_e32 v5, 0x4f7ffffe, v5
	v_cvt_u32_f32_e32 v5, v5
	v_mul_lo_u32 v2, v4, v5
	v_mul_hi_u32 v2, v5, v2
	v_add_u32_e32 v2, v5, v2
	v_mul_hi_u32 v2, v6, v2
	v_mul_lo_u32 v4, v2, v3
	v_sub_u32_e32 v4, v6, v4
	v_add_u32_e32 v5, 1, v2
	v_cmp_ge_u32_e32 vcc, v4, v3
	s_nop 1
	v_cndmask_b32_e32 v2, v2, v5, vcc
	v_sub_u32_e32 v5, v4, v3
	v_cndmask_b32_e32 v4, v4, v5, vcc
	v_add_u32_e32 v5, 1, v2
	v_cmp_ge_u32_e32 vcc, v4, v3
	v_add_u32_e32 v4, 1, v6
	s_nop 0
	v_cndmask_b32_e32 v2, v2, v5, vcc
	v_mul_lo_u32 v5, v3, v2
	v_add_u32_e32 v3, v5, v3
	v_cmp_ne_u32_e32 vcc, v4, v3
	s_and_saveexec_b64 s[8:9], vcc
	s_xor_b64 s[8:9], exec, s[8:9]
	s_cbranch_execz .LBB0_45
	s_waitcnt lgkmcnt(0)
	buffer_inv sc1
	s_add_u32 s16, s60, 0x7400
	s_addc_u32 s17, s61, 0
	v_add_u32_e32 v2, 1, v2
	v_mul_lo_u32 v2, v2, v1
	s_mov_b64 vcc, 0
	s_and_saveexec_b64 s[10:11], vcc
	s_cbranch_execz .LBB0_44
	s_add_u32 s12, s60, 0x4200
	s_addc_u32 s13, s61, 0
	s_mov_b32 s14, 1
	s_mov_b64 s[18:19], 0
	v_mov_b32_e32 v1, 0
	s_branch .LBB0_35

; __device__ __forceinline__ unsigned xb_ld(unsigned* p)              { return __hip_atomic_load(p, __ATOMIC_RELAXED, __HIP_MEMORY_SCOPE_AGENT); }
; __device__ __forceinline__ unsigned xb_add(unsigned* p, unsigned v) { return __hip_atomic_fetch_add(p, v, __ATOMIC_RELAXED, __HIP_MEMORY_SCOPE_AGENT); }
; #define XB_SPIN(cond, bar) do { unsigned _sp = 0; while (cond) { __builtin_amdgcn_s_sleep(1); \
;     if ((++_sp & 255u) == 0u) { if (xb_ld(&(bar)[XB_TMO])) break; if (_sp > XB_SPIN_CAP) { atomicAdd(&(bar)[XB_TMO], 1u); break; } } } } while (0)
; __device__ __forceinline__ void xcd_barrier(const XcdBarrier& b) {
;     ...
;         if (old + 1u == (gen + 1u) * nloc) {
;             __builtin_amdgcn_fence(__ATOMIC_RELEASE, "agent");
;             asm volatile("s_waitcnt vmcnt(0)" ::: "memory");
;             const unsigned og = xb_add(&bar[XB_TOP], 1u);
;             const unsigned tg = og / nx;
;             if (og + 1u == (tg + 1u) * nx) xb_add(&bar[XB_TOPGEN], 1u);
;             else XB_SPIN(xb_ld(&bar[XB_TOPGEN]) == tg, bar);
;             __builtin_amdgcn_fence(__ATOMIC_ACQUIRE, "agent");
.LBB0_45:
	s_andn2_saveexec_b64 s[8:9], s[8:9]
	s_cbranch_execz .LBB0_65
	s_mov_b64 s[8:9], exec
	s_waitcnt lgkmcnt(0)
	s_waitcnt vmcnt(0)
	v_mbcnt_lo_u32_b32 v2, s8, 0
	v_mbcnt_hi_u32_b32 v2, s9, v2
	v_cmp_eq_u32_e32 vcc, 0, v2
	s_and_saveexec_b64 s[10:11], vcc
	s_cbranch_execz .LBB0_48
	s_bcnt1_i32_b64 s8, s[8:9]
	v_mov_b32_e32 v3, 0x7000
	v_mov_b32_e32 v4, s8
	global_atomic_add v3, v4, s[60:61] offset:1024
.LBB0_48:
	s_or_b64 exec, exec, s[10:11]
	v_cvt_f32_u32_e32 v4, v1
	s_waitcnt vmcnt(0)
	v_readfirstlane_b32 s8, v3
	buffer_inv sc1
	s_add_u32 s10, s60, 0x7400
	s_addc_u32 s11, s61, 0
	v_rcp_iflag_f32_e32 v4, v4
	v_add_u32_e32 v2, s8, v2
	v_add_u32_e32 v5, 1, v2
	s_mov_b64 s[12:13], 0
	v_mul_f32_e32 v3, 0x4f7ffffe, v4
	v_cvt_u32_f32_e32 v3, v3
	v_sub_u32_e32 v4, 0, v1
	v_mul_lo_u32 v4, v4, v3
	v_mul_hi_u32 v4, v3, v4
	v_add_u32_e32 v3, v3, v4
	v_mul_hi_u32 v3, v2, v3
	v_mul_lo_u32 v4, v3, v1
	v_sub_u32_e32 v2, v2, v4
	v_add_u32_e32 v6, 1, v3
	v_cmp_ge_u32_e32 vcc, v2, v1
	v_sub_u32_e32 v4, v2, v1
	s_nop 0
	v_cndmask_b32_e32 v3, v3, v6, vcc
	v_cndmask_b32_e32 v2, v2, v4, vcc
	v_add_u32_e32 v4, 1, v3
	v_cmp_ge_u32_e32 vcc, v2, v1
	s_nop 1
	v_cndmask_b32_e32 v4, v3, v4, vcc
	v_mul_lo_u32 v2, v1, v4
	v_add_u32_e32 v1, v2, v1
	s_mov_b64 vcc, 0
	v_mov_b64_e32 v[2:3], s[10:11]
	s_and_saveexec_b64 s[8:9], vcc
	s_cbranch_execz .LBB0_60
	v_mov_b32_e32 v4, v1
	v_mov_b32_e32 v1, 0
	global_load_dword v2, v1, s[10:11] sc1
	s_mov_b64 s[18:19], 0
	s_waitcnt vmcnt(0)
	v_cmp_lt_u32_e32 vcc, v2, v4
	s_and_saveexec_b64 s[16:17], vcc
	s_cbranch_execz .LBB0_59
	s_add_u32 s12, s60, 0x4200
	s_addc_u32 s13, s61, 0
	s_mov_b32 s14, 1
	s_branch .LBB0_52

; #define LAS __attribute__((address_space(3)))
; #define LANE_SETUP() int tid_ = threadIdx.x; asm volatile("" : "+v"(tid_)); const int tid = tid_, lane = tid & 63; (void)lane
; __global__ void __launch_bounds__(NWAVES * 64, 2) fwd(Args a) {
;     ...
;     if (IN(1)) {
;         LANE_SETUP();
;         LAS float* scr = (LAS float*)(lds + RING_OFF + wave * 16384);
;         constexpr int I0 = 16 * 64, I1 = I0 + 8 * 32, I2 = I1 + 16 * 176, I4 = I2 + 44 * 32, I5 = I4 + 4 * 16 * 16, I6 = I5 + 88, I7 = I6 + NBATCH * 16;
;         for (int it = gw; it < I7; it += NGW) {
.LBB0_65:
	s_or_b64 exec, exec, s[4:5]
	s_load_dwordx16 s[4:19], s[0:1], 0x40
	s_waitcnt lgkmcnt(0)
	s_add_u32 s90, s60, 0x700000
	s_addc_u32 s93, s61, 0
	s_add_u32 s82, s60, 0x1400000
	s_addc_u32 s84, s61, 0
	v_writelane_b32 v250, s4, 20
	s_add_u32 s86, s60, 0x60000
	s_addc_u32 s87, s61, 0
	v_writelane_b32 v250, s5, 21
	v_writelane_b32 v250, s6, 22
	v_writelane_b32 v250, s7, 23
	v_writelane_b32 v250, s8, 24
	v_writelane_b32 v250, s9, 25
	v_writelane_b32 v250, s10, 26
	v_writelane_b32 v250, s11, 27
	v_writelane_b32 v250, s12, 28
	v_writelane_b32 v250, s13, 29
	v_writelane_b32 v250, s14, 30
	v_writelane_b32 v250, s15, 31
	v_writelane_b32 v250, s16, 32
	v_writelane_b32 v250, s17, 33
	v_writelane_b32 v250, s18, 34
	v_writelane_b32 v250, s19, 35
	s_add_u32 s14, s60, 0x300000
	s_addc_u32 s15, s61, 0
	s_add_u32 s85, s60, 0x900000
	s_addc_u32 s89, s61, 0
	s_add_u32 s94, s60, 0x1a00000
	s_addc_u32 s95, s61, 0
	s_add_u32 s44, s60, 0x1a10800
	s_addc_u32 s45, s61, 0
	s_add_u32 s40, s60, 0x1a20000
	s_addc_u32 s41, s61, 0
	s_add_u32 s0, s60, 0x1a2a000
	s_addc_u32 s1, s61, 0
	s_add_u32 s68, s60, 0x1a34000
	s_addc_u32 s69, s61, 0
	v_writelane_b32 v250, s0, 36
	s_add_u32 s70, s60, 0x1a3e000
	s_addc_u32 s71, s61, 0
	v_writelane_b32 v250, s1, 37
	v_mov_b32_e32 v8, v0
	s_mov_b32 s99, 0
	s_cmpk_lt_i32 s77, 0x1a78
	v_writelane_b32 v250, s40, 38
	v_and_b32_e32 v1, 63, v8
	s_nop 0
	v_writelane_b32 v250, s41, 39
	s_cbranch_scc0 .LBB0_96
	v_readlane_b32 s4, v250, 0
	v_readlane_b32 s16, v250, 20
	v_lshrrev_b32_e32 v27, 3, v1
	v_and_b32_e32 v6, 7, v8
	v_mov_b32_e32 v3, 0
	v_readlane_b32 s5, v250, 1
	v_readlane_b32 s28, v250, 32
	v_lshlrev_b32_e32 v8, 2, v8
	v_lshlrev_b32_e32 v2, 4, v6
	v_readlane_b32 s8, v250, 4
	v_readlane_b32 s9, v250, 5
	v_lshlrev_b32_e32 v33, 3, v6
	v_mul_u32_u24_e32 v6, 0x420, v6
	v_lshlrev_b32_e32 v7, 2, v27
	v_readlane_b32 s17, v250, 21
	v_readlane_b32 s29, v250, 33
	v_readlane_b32 s30, v250, 34
	v_readlane_b32 s31, v250, 35
	v_lshrrev_b32_e32 v15, 5, v1
	v_and_b32_e32 v8, 0x7c, v8
	v_mov_b32_e32 v9, v3
	s_add_u32 s5, s28, 0x207000
	v_readlane_b32 s0, v250, 18
	v_lshl_add_u64 v[4:5], s[8:9], 0, v[2:3]
	v_add_u32_e32 v28, s78, v2
	v_add3_u32 v34, s78, v6, v7
	v_lshl_add_u64 v[6:7], s[30:31], 0, v[2:3]
	v_add_u32_e32 v35, s78, v8
	v_lshl_add_u64 v[12:13], s[86:87], 0, v[8:9]
	v_lshl_add_u64 v[8:9], s[28:29], 0, v[2:3]
	v_lshl_add_u64 v[10:11], s[16:17], 0, v[2:3]
	v_mul_u32_u24_e32 v2, 0x6e00, v15
	s_addc_u32 s12, s29, 0
	s_lshl_b32 s0, s0, 3
	v_lshlrev_b32_e32 v2, 2, v2
	s_add_i32 s0, s88, s0
	v_readlane_b32 s1, v250, 17
	v_readlane_b32 s7, v250, 3
	v_readlane_b32 s18, v250, 22
	v_readlane_b32 s19, v250, 23
	v_readlane_b32 s20, v250, 24
	v_readlane_b32 s21, v250, 25
	v_readlane_b32 s22, v250, 26
	v_readlane_b32 s23, v250, 27
	v_readlane_b32 s24, v250, 28
	v_readlane_b32 s25, v250, 29
	v_readlane_b32 s26, v250, 30
	v_readlane_b32 s27, v250, 31
	v_mul_u32_u24_e32 v14, 48, v1
	v_lshl_add_u64 v[12:13], v[12:13], 0, v[2:3]
	s_add_i32 s0, s0, s1
	v_mad_u32_u24 v2, v15, 20, s78
	v_or_b32_e32 v26, 0xc00, v1
	v_mul_u32_u24_e32 v29, 0x84, v27
	v_or_b32_e32 v30, 8, v27
	v_or_b32_e32 v31, 16, v27
	v_or_b32_e32 v32, 24, v27
	s_add_i32 s4, s0, 0xffffea80
	s_lshl_b32 s13, s77, 6
	s_lshl_b32 s16, s83, 9
	s_mov_b32 s7, 0
	v_add_u32_e32 v36, 0x2140, v2
	s_movk_i32 s17, 0x5000
	s_movk_i32 s18, 0x7fff
	s_mov_b32 s19, 0xffff0000
	s_movk_i32 s20, 0x3fc0
	s_movk_i32 s21, 0x39c0
	s_movk_i32 s22, 0x3bc0
	s_movk_i32 s23, 0x3dc0
	s_movk_i32 s24, 0x6000
	v_add_u32_e32 v37, s78, v14
	s_mov_b32 s25, 0xc000
	s_mov_b32 s26, 0x12000
	s_mov_b32 s27, 0x18000
	s_mov_b32 s28, 0x1e000
	s_mov_b32 s29, 0x24000
	s_mov_b32 s30, 0x2a000
	s_mov_b32 s31, 0x30000
	v_mov_b32_e32 v38, 0x3f317218
	v_mov_b32_e32 v39, 0x3fb8aa3b
	v_mov_b32_e32 v40, 0x3fc0
	s_mov_b32 s33, s77
	v_readlane_b32 s6, v250, 2
	v_readlane_b32 s10, v250, 6
	v_readlane_b32 s11, v250, 7
	s_mov_b32 s98, s4
	s_branch .LBB0_68

; __global__ void __launch_bounds__(NWAVES * 64, 2) fwd(Args a) {
;     ...
;         for (int it = gw; it < I7; it += NGW) {
;     ...
;             else { const int r = it - I6, b = r / 16, j = 64 * (r % 16) + lane;
;                 g1t[b * D + j] = modv(macc, b_ada, b, 2 * D + j); G2t[b * D + j] = a.in[I_N2G][j] * (modv(macc, b_ada, b, 4 * D + j) + 1.0f); g2t[b * D + j] = modv(macc, b_ada, b, 5 * D + j);
;                 { const float G2v = a.in[I_N2G][j] * (modv(macc, b_ada, b, 4 * D + j) + 1.0f); iG2t[b * D + j] = G2v != 0.f ? 1.0f / G2v : 0.f; } }
.LBB0_68:
	s_sub_u32 s0, s33, 0x500
	s_cmpk_lt_u32 s0, 0xb00
	s_cselect_b32 s0, 1, 0
	s_cmpk_gt_u32 s33, 0x19d7
	s_cselect_b32 s1, 1, 0
	s_or_b32 s0, s0, s1
	s_cmp_lg_u32 s0, s99
	s_cbranch_scc1 .LBB0_67
	s_cmpk_gt_i32 s33, 0x3ff
	s_mov_b64 s[0:1], -1
	s_cbranch_scc0 .LBB0_94
	s_cmpk_gt_u32 s33, 0x4ff
	s_cbranch_scc0 .LBB0_91
	s_cmpk_gt_u32 s33, 0xfff
	s_cbranch_scc0 .LBB0_86
	s_cmpk_gt_u32 s33, 0x157f
	s_cbranch_scc0 .LBB0_83
	s_cmpk_gt_u32 s33, 0x197f
	s_cbranch_scc0 .LBB0_78
	s_cmpk_gt_u32 s33, 0x19d7
	s_cbranch_scc0 .LBB0_75
	s_add_i32 s0, s33, 0xffffe628
	s_lshr_b32 s1, s0, 4
	s_lshl_b32 s0, s0, 6
	s_and_b32 s0, s0, 0x3c0
	v_or_b32_e32 v20, s0, v1
	v_or_b32_e32 v16, 0x800, v20
	s_mul_i32 s0, s1, 0x1800
	v_add_u32_e32 v2, s0, v16
	v_lshl_add_u64 v[14:15], v[2:3], 2, s[72:73]
	v_lshlrev_b32_e32 v2, 2, v16
	global_load_dword v21, v2, s[46:47]
	global_load_dword v22, v[14:15], off
	v_or_b32_e32 v16, 0x1000, v20
	v_lshl_or_b32 v2, s1, 10, v20
	v_lshlrev_b64 v[14:15], 2, v[2:3]
	v_add_u32_e32 v2, s0, v16
	v_lshlrev_b32_e32 v23, 2, v16
	v_lshl_add_u64 v[16:17], s[40:41], 0, v[14:15]
	v_lshl_add_u64 v[18:19], v[2:3], 2, s[72:73]
	v_lshlrev_b32_e32 v25, 2, v20
	v_readlane_b32 s8, v250, 36
	v_readlane_b32 s9, v250, 37
	s_waitcnt vmcnt(0)
	v_add_f32_e32 v2, v22, v21
	global_store_dword v[16:17], v2, off
	global_load_dword v22, v[18:19], off
	global_load_dword v24, v23, s[46:47]
	global_load_dword v41, v25, s[50:51]
	v_or_b32_e32 v2, 0x1400, v20
	v_lshlrev_b32_e32 v42, 2, v2
	v_add_u32_e32 v2, s0, v2
	v_lshl_add_u64 v[20:21], v[2:3], 2, s[72:73]
	v_lshl_add_u64 v[16:17], s[8:9], 0, v[14:15]
	s_waitcnt vmcnt(1)
	v_add_f32_e32 v2, v22, v24
	v_add_f32_e32 v2, 1.0, v2
	s_waitcnt vmcnt(0)
	v_mul_f32_e32 v2, v41, v2
	global_store_dword v[16:17], v2, off
	global_load_dword v2, v[20:21], off
	s_nop 0
	global_load_dword v20, v42, s[46:47]
	v_lshl_add_u64 v[16:17], s[68:69], 0, v[14:15]
	v_lshl_add_u64 v[14:15], s[70:71], 0, v[14:15]
	s_waitcnt vmcnt(0)
	v_add_f32_e32 v2, v2, v20
	global_store_dword v[16:17], v2, off
	global_load_dword v2, v[18:19], off
	s_nop 0
	global_load_dword v16, v23, s[46:47]
	global_load_dword v17, v25, s[50:51]
	s_waitcnt vmcnt(1)
	v_add_f32_e32 v2, v2, v16
	v_add_f32_e32 v2, 1.0, v2
	s_waitcnt vmcnt(0)
	v_mul_f32_e32 v2, v17, v2
	v_div_scale_f32 v16, s[0:1], v2, v2, 1.0
	v_rcp_f32_e32 v17, v16
	v_div_scale_f32 v18, vcc, 1.0, v2, 1.0
	s_mov_b64 s[0:1], 0
	v_fma_f32 v19, -v16, v17, 1.0
	v_fmac_f32_e32 v17, v19, v17
	v_mul_f32_e32 v19, v18, v17
	v_fma_f32 v20, -v16, v19, v18
	v_fmac_f32_e32 v19, v20, v17
	v_fma_f32 v16, -v16, v19, v18
	v_div_fmas_f32 v16, v16, v17, v19
	v_div_fixup_f32 v16, v16, v2, 1.0
	v_cmp_neq_f32_e32 vcc, 0, v2
	s_nop 1
	v_cndmask_b32_e32 v2, 0, v16, vcc
	global_store_dword v[14:15], v2, off

; #define LAS __attribute__((address_space(3)))
; __device__ __forceinline__ unsigned xb_ld(unsigned* p)              { return __hip_atomic_load(p, __ATOMIC_RELAXED, __HIP_MEMORY_SCOPE_AGENT); }
; #define XB_SPIN(cond, bar) do { unsigned _sp = 0; while (cond) { __builtin_amdgcn_s_sleep(1); \
;     if ((++_sp & 255u) == 0u) { if (xb_ld(&(bar)[XB_TMO])) break; if (_sp > XB_SPIN_CAP) { atomicAdd(&(bar)[XB_TMO], 1u); break; } } } } while (0)
; #define LANE_SETUP() int tid_ = threadIdx.x; asm volatile("" : "+v"(tid_)); const int tid = tid_, lane = tid & 63; (void)lane
; #define SEAM(k) do { if ((k) < 2) xcd_barrier(bar); else xcd_barrier(barg); } while (0)
; __device__ __forceinline__ void xcd_barrier(const XcdBarrier& b) {
;     ...
;             XB_SPIN(xb_ld(&bar[XB_XGEN(b.x)]) == gen, bar);
;             __builtin_amdgcn_fence(__ATOMIC_ACQUIRE, "agent");
;             asm volatile("s_waitcnt vmcnt(0)" ::: "memory");
; __global__ void __launch_bounds__(NWAVES * 64, 2) fwd(Args a) {
;     ...
;     SEAM(0);
;     for (int rep = 0; rep <= PROBE_REPS(1); ++rep) { const float asc = rep ? 0.f : 1.f; (void)asc;
;     if (IN(1)) {
;         LANE_SETUP();
;         LAS float* scr = (LAS float*)(lds + RING_OFF + wave * 16384);
;         constexpr int I0 = 16 * 64, I1 = I0 + 8 * 32, I2 = I1 + 16 * 176, I4 = I2 + 44 * 32, I5 = I4 + 4 * 16 * 16, I6 = I5 + 88, I7 = I6 + NBATCH * 16;
;         for (int it = gw; it < I7; it += NGW) {
.LBB0_96:
	s_cmp_lg_u32 s99, 0
	s_cbranch_scc1 .Lp1_rows
	s_and_saveexec_b64 s[0:1], s[80:81]
	s_cbranch_execz .Lp1_poll_done
	v_mov_b32_e32 v240, 0x26164
	ds_read_b32 v241, v240
	v_readlane_b32 s100, v250, 14
	s_nop 1
	v_mov_b32_e32 v242, s100
	v_readlane_b32 s100, v250, 15
	s_nop 1
	v_mov_b32_e32 v243, s100
	v_add_co_u32_e32 v242, vcc, 0x7400, v242
	s_nop 1
	v_addc_co_u32_e32 v243, vcc, 0, v243, vcc
	s_mov_b32 s13, 0
	s_waitcnt lgkmcnt(0)
.Lp1_spin:
	global_load_dword v244, v[242:243], off sc1
	s_waitcnt vmcnt(0)
	v_cmp_lt_u32_e32 vcc, v244, v241
	s_cbranch_vccz .Lp1_released
	s_sleep 1
	s_add_i32 s13, s13, 1
	s_cmp_lt_u32 s13, 0x4000
	s_cbranch_scc1 .Lp1_spin
.Lp1_released:
	s_and_b32 s100, s101, 7
	s_lshl_b32 s100, s100, 2
	s_add_i32 s100, s100, 0x10c00
	v_mov_b32_e32 v245, s100
	v_add_co_u32_e32 v246, vcc, v242, v245
	s_nop 1
	v_addc_co_u32_e32 v247, vcc, 0, v243, vcc
	global_load_dword v248, v[246:247], off sc1
	s_waitcnt vmcnt(0)
	v_add_u32_e32 v249, -1, v248
	v_and_b32_e32 v249, v249, v248
	v_cmp_ne_u32_e32 vcc, 0, v249
	s_cbranch_vccz .Lp1_poll_done
	v_add_co_u32_e32 v246, vcc, 0x11400, v242
	s_nop 1
	v_addc_co_u32_e32 v247, vcc, 0, v243, vcc
	v_mov_b32_e32 v248, 1
	global_atomic_add v[246:247], v248, off
.Lp1_poll_done:
	s_or_b64 exec, exec, s[0:1]
	s_barrier
	s_mov_b32 s99, 1
	s_cmpk_lt_i32 s77, 0x1a78
	s_cbranch_scc0 .Lp1_rows
	s_mov_b32 s33, s77
	s_mov_b32 s4, s98
	s_lshl_b32 s13, s77, 6
	s_branch .LBB0_68
